# k9 + counted vmcnt waits in the first half of the merged-GEMM gate epilogue
# baseline (speedup 1.0000x reference)
; __device__ __forceinline__ float clampg(unsigned bits) { return __uint_as_float(bits > 0x0da24260u ? bits : 0x0da24260u); }
;     __device__ __forceinline__ void operator()(acc_t& acc, const Unit& u, int wr, int wc, int fr, int fq) const {
;     ...
;             for (int m = 0; m < 4; ++m)
; #pragma unroll
;                 for (int bj = 0; bj < 2; ++bj) {
;                     const u32x4 a = ga[m][bj]; float f[8] = {clampg(a.x << 16), clampg(a.x & 0xffff0000u), clampg(a.y << 16), clampg(a.y & 0xffff0000u), clampg(a.z << 16), clampg(a.z & 0xffff0000u), clampg(a.w << 16), clampg(a.w & 0xffff0000u)};
;                     if (br < 2) { const u32x4 b = gb[m][bj]; const float d[8] = {clampg(b.x << 16), clampg(b.x & 0xffff0000u), clampg(b.y << 16), clampg(b.y & 0xffff0000u), clampg(b.z << 16), clampg(b.z & 0xffff0000u), clampg(b.w << 16), clampg(b.w & 0xffff0000u)};
.LBB0_597:
	s_waitcnt vmcnt(7)
	v_lshlrev_b32_e32 v202, 16, v190
	v_and_b32_e32 v190, 0xffff0000, v190
	v_max_u32_e32 v205, 0xda24260, v190
	v_lshlrev_b32_e32 v190, 16, v191
	v_max_u32_e32 v204, 0xda24260, v202
	v_max_u32_e32 v202, 0xda24260, v190
	v_and_b32_e32 v190, 0xffff0000, v191
	v_max_u32_e32 v203, 0xda24260, v190
	v_lshlrev_b32_e32 v190, 16, v192
	v_max_u32_e32 v206, 0xda24260, v190
	v_and_b32_e32 v190, 0xffff0000, v192
	v_max_u32_e32 v207, 0xda24260, v190
	v_lshlrev_b32_e32 v190, 16, v193
	v_and_b32_e32 v191, 0xffff0000, v193
	v_cndmask_b32_e64 v192, 0, 1, s[2:3]
	v_max_u32_e32 v190, 0xda24260, v190
	v_max_u32_e32 v191, 0xda24260, v191
	v_cmp_ne_u32_e64 s[6:7], 1, v192
	s_andn2_b64 vcc, exec, s[2:3]
	s_mov_b64 s[2:3], -1
	s_cbranch_vccnz .LBB0_599
	s_mov_b64 s[2:3], 0

; __device__ __forceinline__ float clampg(unsigned bits) { return __uint_as_float(bits > 0x0da24260u ? bits : 0x0da24260u); }
;     __device__ __forceinline__ void operator()(acc_t& acc, const Unit& u, int wr, int wc, int fr, int fq) const {
;     ...
;             for (int m = 0; m < 4; ++m)
; #pragma unroll
;                 for (int bj = 0; bj < 2; ++bj) {
;                     const u32x4 a = ga[m][bj]; float f[8] = {clampg(a.x << 16), clampg(a.x & 0xffff0000u), clampg(a.y << 16), clampg(a.y & 0xffff0000u), clampg(a.z << 16), clampg(a.z & 0xffff0000u), clampg(a.w << 16), clampg(a.w & 0xffff0000u)};
;                     if (br < 2) { const u32x4 b = gb[m][bj]; const float d[8] = {clampg(b.x << 16), clampg(b.x & 0xffff0000u), clampg(b.y << 16), clampg(b.y & 0xffff0000u), clampg(b.z << 16), clampg(b.z & 0xffff0000u), clampg(b.w << 16), clampg(b.w & 0xffff0000u)};
.LBB0_604:
	s_waitcnt vmcnt(6)
	v_lshlrev_b32_e32 v190, 16, v186
	v_and_b32_e32 v186, 0xffff0000, v186
	v_max_u32_e32 v193, 0xda24260, v186
	v_lshlrev_b32_e32 v186, 16, v187
	v_max_u32_e32 v192, 0xda24260, v190
	v_max_u32_e32 v190, 0xda24260, v186
	v_and_b32_e32 v186, 0xffff0000, v187
	v_max_u32_e32 v191, 0xda24260, v186
	v_lshlrev_b32_e32 v186, 16, v188
	v_max_u32_e32 v202, 0xda24260, v186
	v_and_b32_e32 v186, 0xffff0000, v188
	v_max_u32_e32 v203, 0xda24260, v186
	v_lshlrev_b32_e32 v186, 16, v189
	v_and_b32_e32 v187, 0xffff0000, v189
	v_max_u32_e32 v186, 0xda24260, v186
	v_max_u32_e32 v187, 0xda24260, v187
	s_and_b64 vcc, exec, s[6:7]
	s_mov_b64 s[2:3], -1
	s_cbranch_vccnz .LBB0_606
	s_mov_b64 s[2:3], 0

; __device__ __forceinline__ float clampg(unsigned bits) { return __uint_as_float(bits > 0x0da24260u ? bits : 0x0da24260u); }
;     __device__ __forceinline__ void operator()(acc_t& acc, const Unit& u, int wr, int wc, int fr, int fq) const {
;     ...
;             for (int m = 0; m < 4; ++m)
; #pragma unroll
;                 for (int bj = 0; bj < 2; ++bj) {
;                     const u32x4 a = ga[m][bj]; float f[8] = {clampg(a.x << 16), clampg(a.x & 0xffff0000u), clampg(a.y << 16), clampg(a.y & 0xffff0000u), clampg(a.z << 16), clampg(a.z & 0xffff0000u), clampg(a.w << 16), clampg(a.w & 0xffff0000u)};
;                     if (br < 2) { const u32x4 b = gb[m][bj]; const float d[8] = {clampg(b.x << 16), clampg(b.x & 0xffff0000u), clampg(b.y << 16), clampg(b.y & 0xffff0000u), clampg(b.z << 16), clampg(b.z & 0xffff0000u), clampg(b.w << 16), clampg(b.w & 0xffff0000u)};
.LBB0_611:
	s_waitcnt vmcnt(5)
	v_lshlrev_b32_e32 v186, 16, v182
	v_and_b32_e32 v182, 0xffff0000, v182
	v_max_u32_e32 v189, 0xda24260, v182
	v_lshlrev_b32_e32 v182, 16, v183
	v_max_u32_e32 v188, 0xda24260, v186
	v_max_u32_e32 v186, 0xda24260, v182
	v_and_b32_e32 v182, 0xffff0000, v183
	v_max_u32_e32 v187, 0xda24260, v182
	v_lshlrev_b32_e32 v182, 16, v184
	v_max_u32_e32 v190, 0xda24260, v182
	v_and_b32_e32 v182, 0xffff0000, v184
	v_max_u32_e32 v191, 0xda24260, v182
	v_lshlrev_b32_e32 v182, 16, v185
	v_and_b32_e32 v183, 0xffff0000, v185
	v_max_u32_e32 v182, 0xda24260, v182
	v_max_u32_e32 v183, 0xda24260, v183
	s_and_b64 vcc, exec, s[6:7]
	s_mov_b64 s[2:3], -1
	s_cbranch_vccnz .LBB0_613
	s_mov_b64 s[2:3], 0

; __device__ __forceinline__ float clampg(unsigned bits) { return __uint_as_float(bits > 0x0da24260u ? bits : 0x0da24260u); }
;     __device__ __forceinline__ void operator()(acc_t& acc, const Unit& u, int wr, int wc, int fr, int fq) const {
;     ...
;             for (int m = 0; m < 4; ++m)
; #pragma unroll
;                 for (int bj = 0; bj < 2; ++bj) {
;                     const u32x4 a = ga[m][bj]; float f[8] = {clampg(a.x << 16), clampg(a.x & 0xffff0000u), clampg(a.y << 16), clampg(a.y & 0xffff0000u), clampg(a.z << 16), clampg(a.z & 0xffff0000u), clampg(a.w << 16), clampg(a.w & 0xffff0000u)};
;                     if (br < 2) { const u32x4 b = gb[m][bj]; const float d[8] = {clampg(b.x << 16), clampg(b.x & 0xffff0000u), clampg(b.y << 16), clampg(b.y & 0xffff0000u), clampg(b.z << 16), clampg(b.z & 0xffff0000u), clampg(b.w << 16), clampg(b.w & 0xffff0000u)};
.LBB0_618:
	s_waitcnt vmcnt(4)
	v_lshlrev_b32_e32 v182, 16, v178
	v_and_b32_e32 v178, 0xffff0000, v178
	v_max_u32_e32 v185, 0xda24260, v178
	v_lshlrev_b32_e32 v178, 16, v179
	v_max_u32_e32 v184, 0xda24260, v182
	v_max_u32_e32 v182, 0xda24260, v178
	v_and_b32_e32 v178, 0xffff0000, v179
	v_max_u32_e32 v183, 0xda24260, v178
	v_lshlrev_b32_e32 v178, 16, v180
	v_max_u32_e32 v186, 0xda24260, v178
	v_and_b32_e32 v178, 0xffff0000, v180
	v_max_u32_e32 v187, 0xda24260, v178
	v_lshlrev_b32_e32 v178, 16, v181
	v_and_b32_e32 v179, 0xffff0000, v181
	v_max_u32_e32 v178, 0xda24260, v178
	v_max_u32_e32 v179, 0xda24260, v179
	s_and_b64 vcc, exec, s[6:7]
	s_mov_b64 s[2:3], -1
	s_cbranch_vccnz .LBB0_620
	s_mov_b64 s[2:3], 0

; __device__ __forceinline__ float clampg(unsigned bits) { return __uint_as_float(bits > 0x0da24260u ? bits : 0x0da24260u); }
;     __device__ __forceinline__ void operator()(acc_t& acc, const Unit& u, int wr, int wc, int fr, int fq) const {
;     ...
;             for (int m = 0; m < 4; ++m)
; #pragma unroll
;                 for (int bj = 0; bj < 2; ++bj) {
;                     const u32x4 a = ga[m][bj]; float f[8] = {clampg(a.x << 16), clampg(a.x & 0xffff0000u), clampg(a.y << 16), clampg(a.y & 0xffff0000u), clampg(a.z << 16), clampg(a.z & 0xffff0000u), clampg(a.w << 16), clampg(a.w & 0xffff0000u)};
;                     if (br < 2) { const u32x4 b = gb[m][bj]; const float d[8] = {clampg(b.x << 16), clampg(b.x & 0xffff0000u), clampg(b.y << 16), clampg(b.y & 0xffff0000u), clampg(b.z << 16), clampg(b.z & 0xffff0000u), clampg(b.w << 16), clampg(b.w & 0xffff0000u)};
.LBB0_625:
	s_waitcnt vmcnt(3)
	v_lshlrev_b32_e32 v178, 16, v174
	v_and_b32_e32 v174, 0xffff0000, v174
	v_max_u32_e32 v181, 0xda24260, v174
	v_lshlrev_b32_e32 v174, 16, v175
	v_max_u32_e32 v180, 0xda24260, v178
	v_max_u32_e32 v178, 0xda24260, v174
	v_and_b32_e32 v174, 0xffff0000, v175
	v_max_u32_e32 v179, 0xda24260, v174
	v_lshlrev_b32_e32 v174, 16, v176
	v_max_u32_e32 v182, 0xda24260, v174
	v_and_b32_e32 v174, 0xffff0000, v176
	v_max_u32_e32 v183, 0xda24260, v174
	v_lshlrev_b32_e32 v174, 16, v177
	v_and_b32_e32 v175, 0xffff0000, v177
	v_max_u32_e32 v174, 0xda24260, v174
	v_max_u32_e32 v175, 0xda24260, v175
	s_and_b64 vcc, exec, s[6:7]
	s_mov_b64 s[2:3], -1
	s_cbranch_vccnz .LBB0_627
	s_mov_b64 s[2:3], 0

; __device__ __forceinline__ float clampg(unsigned bits) { return __uint_as_float(bits > 0x0da24260u ? bits : 0x0da24260u); }
;     __device__ __forceinline__ void operator()(acc_t& acc, const Unit& u, int wr, int wc, int fr, int fq) const {
;     ...
;             for (int m = 0; m < 4; ++m)
; #pragma unroll
;                 for (int bj = 0; bj < 2; ++bj) {
;                     const u32x4 a = ga[m][bj]; float f[8] = {clampg(a.x << 16), clampg(a.x & 0xffff0000u), clampg(a.y << 16), clampg(a.y & 0xffff0000u), clampg(a.z << 16), clampg(a.z & 0xffff0000u), clampg(a.w << 16), clampg(a.w & 0xffff0000u)};
;                     if (br < 2) { const u32x4 b = gb[m][bj]; const float d[8] = {clampg(b.x << 16), clampg(b.x & 0xffff0000u), clampg(b.y << 16), clampg(b.y & 0xffff0000u), clampg(b.z << 16), clampg(b.z & 0xffff0000u), clampg(b.w << 16), clampg(b.w & 0xffff0000u)};
.LBB0_632:
	s_waitcnt vmcnt(2)
	v_lshlrev_b32_e32 v174, 16, v170
	v_and_b32_e32 v170, 0xffff0000, v170
	v_max_u32_e32 v177, 0xda24260, v170
	v_lshlrev_b32_e32 v170, 16, v171
	v_max_u32_e32 v176, 0xda24260, v174
	v_max_u32_e32 v174, 0xda24260, v170
	v_and_b32_e32 v170, 0xffff0000, v171
	v_max_u32_e32 v175, 0xda24260, v170
	v_lshlrev_b32_e32 v170, 16, v172
	v_max_u32_e32 v178, 0xda24260, v170
	v_and_b32_e32 v170, 0xffff0000, v172
	v_max_u32_e32 v179, 0xda24260, v170
	v_lshlrev_b32_e32 v170, 16, v173
	v_and_b32_e32 v171, 0xffff0000, v173
	v_max_u32_e32 v170, 0xda24260, v170
	v_max_u32_e32 v171, 0xda24260, v171
	s_and_b64 vcc, exec, s[6:7]
	s_mov_b64 s[2:3], -1
	s_cbranch_vccnz .LBB0_634
	s_mov_b64 s[2:3], 0

; __device__ __forceinline__ float clampg(unsigned bits) { return __uint_as_float(bits > 0x0da24260u ? bits : 0x0da24260u); }
;     __device__ __forceinline__ void operator()(acc_t& acc, const Unit& u, int wr, int wc, int fr, int fq) const {
;     ...
;             for (int m = 0; m < 4; ++m)
; #pragma unroll
;                 for (int bj = 0; bj < 2; ++bj) {
;                     const u32x4 a = ga[m][bj]; float f[8] = {clampg(a.x << 16), clampg(a.x & 0xffff0000u), clampg(a.y << 16), clampg(a.y & 0xffff0000u), clampg(a.z << 16), clampg(a.z & 0xffff0000u), clampg(a.w << 16), clampg(a.w & 0xffff0000u)};
;                     if (br < 2) { const u32x4 b = gb[m][bj]; const float d[8] = {clampg(b.x << 16), clampg(b.x & 0xffff0000u), clampg(b.y << 16), clampg(b.y & 0xffff0000u), clampg(b.z << 16), clampg(b.z & 0xffff0000u), clampg(b.w << 16), clampg(b.w & 0xffff0000u)};
.LBB0_639:
	s_waitcnt vmcnt(1)
	v_lshlrev_b32_e32 v170, 16, v166
	v_and_b32_e32 v166, 0xffff0000, v166
	v_max_u32_e32 v173, 0xda24260, v166
	v_lshlrev_b32_e32 v166, 16, v167
	v_max_u32_e32 v172, 0xda24260, v170
	v_max_u32_e32 v170, 0xda24260, v166
	v_and_b32_e32 v166, 0xffff0000, v167
	v_max_u32_e32 v171, 0xda24260, v166
	v_lshlrev_b32_e32 v166, 16, v168
	v_max_u32_e32 v174, 0xda24260, v166
	v_and_b32_e32 v166, 0xffff0000, v168
	v_max_u32_e32 v175, 0xda24260, v166
	v_lshlrev_b32_e32 v166, 16, v169
	v_and_b32_e32 v167, 0xffff0000, v169
	v_max_u32_e32 v166, 0xda24260, v166
	v_max_u32_e32 v167, 0xda24260, v167
	s_and_b64 vcc, exec, s[6:7]
	s_mov_b64 s[2:3], -1
	s_cbranch_vccnz .LBB0_641
	s_mov_b64 s[2:3], 0

; __device__ __forceinline__ float clampg(unsigned bits) { return __uint_as_float(bits > 0x0da24260u ? bits : 0x0da24260u); }
;     __device__ __forceinline__ void operator()(acc_t& acc, const Unit& u, int wr, int wc, int fr, int fq) const {
;     ...
;             for (int m = 0; m < 4; ++m)
; #pragma unroll
;                 for (int bj = 0; bj < 2; ++bj) {
;                     const u32x4 a = ga[m][bj]; float f[8] = {clampg(a.x << 16), clampg(a.x & 0xffff0000u), clampg(a.y << 16), clampg(a.y & 0xffff0000u), clampg(a.z << 16), clampg(a.z & 0xffff0000u), clampg(a.w << 16), clampg(a.w & 0xffff0000u)};
;                     if (br < 2) { const u32x4 b = gb[m][bj]; const float d[8] = {clampg(b.x << 16), clampg(b.x & 0xffff0000u), clampg(b.y << 16), clampg(b.y & 0xffff0000u), clampg(b.z << 16), clampg(b.z & 0xffff0000u), clampg(b.w << 16), clampg(b.w & 0xffff0000u)};
.LBB0_646:
	s_waitcnt vmcnt(0)
	v_lshlrev_b32_e32 v166, 16, v162
	v_and_b32_e32 v162, 0xffff0000, v162
	v_max_u32_e32 v169, 0xda24260, v162
	v_lshlrev_b32_e32 v162, 16, v163
	v_max_u32_e32 v168, 0xda24260, v166
	v_max_u32_e32 v166, 0xda24260, v162
	v_and_b32_e32 v162, 0xffff0000, v163
	v_max_u32_e32 v167, 0xda24260, v162
	v_lshlrev_b32_e32 v162, 16, v164
	v_max_u32_e32 v170, 0xda24260, v162
	v_and_b32_e32 v162, 0xffff0000, v164
	v_max_u32_e32 v171, 0xda24260, v162
	v_lshlrev_b32_e32 v162, 16, v165
	v_and_b32_e32 v163, 0xffff0000, v165
	v_max_u32_e32 v162, 0xda24260, v162
	v_max_u32_e32 v163, 0xda24260, v163
	s_and_b64 vcc, exec, s[6:7]
	s_mov_b64 s[2:3], -1
	s_cbranch_vccnz .LBB0_648
	s_mov_b64 s[2:3], 0
